# EpiRes GEMM epilogues de-serialized: 8 residual/gate loads per row group hoisted into free fragment registers with counted vmcnt instead of load-wait(0)-store ladder
# speedup vs baseline: 1.0012x; 1.0012x over previous
;   __device__ __forceinline__ void operator()(const f32x4 (&acc)[4][4], int row0w, int col0w, int l15, int quad) const {
; #pragma unroll
;     for (int i = 0; i < 4; ++i) {
;       const int row = row0w + i * 16 + l15;
;       const int b = row / TPB, kidx = row - b * TPB;
;       const bool isc = kidx < 256;
;       const size_t off = isc ? (size_t)(b * 256 + kidx) * DM : (size_t)(b * 16384 + kidx - 256) * DM;
;       const float* src = (isc ? ctx_src : lat_src) + off;
;       float* dst = (isc ? ctx_dst : lat_dst) + off;
;       const float* g = gate + (isc ? 2 : b) * 6144;
; #pragma unroll
;       for (int j = 0; j < 4; ++j) {
;         const int n = col0w + j * 16 + quad * 4;
;         const float4 xo = *(const float4*)(src + n);
;         const float4 g4 = *(const float4*)(g + n);
;         float4 o;
;         o.x = xo.x + g4.x * acc[i][j][0];
;         o.y = xo.y + g4.y * acc[i][j][1];
;         o.z = xo.z + g4.z * acc[i][j][2];
;         o.w = xo.w + g4.w * acc[i][j][3];
;         *(float4*)(dst + n) = o;
;       }
;     }
;   }
.LBB0_435:
	s_or_b64 exec, exec, s[0:1]
	v_mul_i32_i24_e32 v19, 0x1800, v19
	v_cndmask_b32_e32 v22, v19, v184, vcc
	v_ashrrev_i32_e32 v19, 31, v18
	v_lshlrev_b64 v[18:19], 12, v[18:19]
	v_ashrrev_i32_e32 v23, 31, v22
	v_lshl_add_u64 v[16:17], v[16:17], 0, v[18:19]
	v_lshl_add_u64 v[18:19], v[20:21], 0, v[18:19]
	v_lshl_add_u64 v[20:21], v[22:23], 2, s[6:7]
	v_lshl_add_u64 v[24:25], v[16:17], 0, v[64:65]
	v_lshl_add_u64 v[26:27], v[20:21], 0, v[64:65]
	v_lshl_add_u64 v[28:29], v[18:19], 0, v[64:65]
	global_load_dwordx4 v[156:159], v[24:25], off
	global_load_dwordx4 v[152:155], v[26:27], off
	global_load_dwordx4 v[132:135], v[24:25], off offset:64
	global_load_dwordx4 v[124:127], v[26:27], off offset:64
	global_load_dwordx4 v[136:139], v[24:25], off offset:128
	global_load_dwordx4 v[140:143], v[26:27], off offset:128
	global_load_dwordx4 v[144:147], v[24:25], off offset:192
	global_load_dwordx4 v[148:151], v[26:27], off offset:192
	s_add_i32 s22, s22, s90
	s_add_i32 s2, s2, s90
	s_cmp_ge_i32 s22, s84
	s_waitcnt vmcnt(6)
	v_pk_fma_f32 v[12:13], v[12:13], v[152:153], v[156:157]
	s_waitcnt vmcnt(6)
	v_pk_fma_f32 v[14:15], v[14:15], v[154:155], v[158:159]
	global_store_dwordx4 v[28:29], v[12:15], off
	s_waitcnt vmcnt(5)
	v_pk_fma_f32 v[8:9], v[8:9], v[124:125], v[132:133]
	s_waitcnt vmcnt(5)
	v_pk_fma_f32 v[10:11], v[10:11], v[126:127], v[134:135]
	global_store_dwordx4 v[28:29], v[8:11], off offset:64
	s_waitcnt vmcnt(4)
	v_pk_fma_f32 v[4:5], v[4:5], v[140:141], v[136:137]
	s_waitcnt vmcnt(4)
	v_pk_fma_f32 v[6:7], v[6:7], v[142:143], v[138:139]
	global_store_dwordx4 v[28:29], v[4:7], off offset:128
	s_waitcnt vmcnt(3)
	v_pk_fma_f32 v[0:1], v[0:1], v[148:149], v[144:145]
	s_waitcnt vmcnt(3)
	v_pk_fma_f32 v[2:3], v[2:3], v[150:151], v[146:147]
	global_store_dwordx4 v[28:29], v[0:3], off offset:192
	s_cbranch_scc1 .LBB0_456

;   __device__ __forceinline__ void operator()(const f32x4 (&acc)[4][4], int row0w, int col0w, int l15, int quad) const {
; #pragma unroll
;     for (int i = 0; i < 4; ++i) {
;       const int row = row0w + i * 16 + l15;
;       const int b = row / TPB, kidx = row - b * TPB;
;       const bool isc = kidx < 256;
;       const size_t off = isc ? (size_t)(b * 256 + kidx) * DM : (size_t)(b * 16384 + kidx - 256) * DM;
;       const float* src = (isc ? ctx_src : lat_src) + off;
;       float* dst = (isc ? ctx_dst : lat_dst) + off;
;       const float* g = gate + (isc ? 2 : b) * 6144;
; #pragma unroll
;       for (int j = 0; j < 4; ++j) {
;         const int n = col0w + j * 16 + quad * 4;
;         const float4 xo = *(const float4*)(src + n);
;         const float4 g4 = *(const float4*)(g + n);
;         float4 o;
;         o.x = xo.x + g4.x * acc[i][j][0];
;         o.y = xo.y + g4.y * acc[i][j][1];
;         o.z = xo.z + g4.z * acc[i][j][2];
;         o.w = xo.w + g4.w * acc[i][j][3];
;         *(float4*)(dst + n) = o;
;       }
;     }
;   }
.LBB0_440:
	s_waitcnt vmcnt(6)
	v_add_u32_e32 v70, s0, v174
	v_mul_hi_i32 v64, v70, s11
	v_lshrrev_b32_e32 v65, 31, v64
	v_ashrrev_i32_e32 v64, 13, v64
	v_add_u32_e32 v71, v64, v65
	v_mad_i32_i24 v67, v71, s16, v70
	v_cmp_gt_i32_e32 vcc, s17, v67
	v_cmp_lt_i32_e64 s[0:1], s18, v67
	v_mov_b64_e32 v[64:65], s[40:41]
	s_and_saveexec_b64 s[12:13], s[0:1]
	s_xor_b64 s[0:1], exec, s[12:13]
	v_lshlrev_b32_e32 v64, 14, v71
	v_add3_u32 v66, v64, v67, s19
	v_mov_b64_e32 v[64:65], s[36:37]
	s_or_saveexec_b64 s[0:1], s[0:1]
	v_mov_b64_e32 v[68:69], s[92:93]
	s_xor_b64 exec, exec, s[0:1]
	v_lshl_add_u32 v66, v71, 8, v67
	v_mov_b64_e32 v[68:69], s[68:69]
	s_or_b64 exec, exec, s[0:1]
	v_ashrrev_i32_e32 v67, 31, v66
	v_lshlrev_b64 v[66:67], 12, v[66:67]
	s_waitcnt vmcnt(3)
	v_lshl_add_u64 v[74:75], v[64:65], 0, v[66:67]
	v_mul_i32_i24_e32 v64, 0x1800, v71
	v_or_b32_e32 v72, s8, v176
	v_cndmask_b32_e32 v64, v64, v184, vcc
	v_ashrrev_i32_e32 v73, 31, v72
	v_ashrrev_i32_e32 v65, 31, v64
	v_lshl_add_u64 v[66:67], v[68:69], 0, v[66:67]
	v_lshl_add_u64 v[68:69], v[64:65], 2, s[6:7]
	v_lshlrev_b64 v[64:65], 2, v[72:73]
	s_waitcnt vmcnt(2)
	v_lshl_add_u64 v[76:77], v[74:75], 0, v[64:65]
	v_lshl_add_u64 v[78:79], v[68:69], 0, v[64:65]
	v_lshl_add_u64 v[80:81], v[66:67], 0, v[64:65]
	global_load_dwordx4 v[156:159], v[76:77], off
	global_load_dwordx4 v[152:155], v[78:79], off
	global_load_dwordx4 v[132:135], v[76:77], off offset:64
	global_load_dwordx4 v[124:127], v[78:79], off offset:64
	global_load_dwordx4 v[136:139], v[76:77], off offset:128
	global_load_dwordx4 v[140:143], v[78:79], off offset:128
	global_load_dwordx4 v[144:147], v[76:77], off offset:192
	global_load_dwordx4 v[148:151], v[78:79], off offset:192
	s_waitcnt vmcnt(6)
	v_pk_fma_f32 v[60:61], v[60:61], v[152:153], v[156:157]
	s_waitcnt vmcnt(6)
	v_pk_fma_f32 v[62:63], v[62:63], v[154:155], v[158:159]
	global_store_dwordx4 v[80:81], v[60:63], off
	s_waitcnt vmcnt(5)
	v_pk_fma_f32 v[56:57], v[56:57], v[124:125], v[132:133]
	s_waitcnt vmcnt(5)
	v_pk_fma_f32 v[58:59], v[58:59], v[126:127], v[134:135]
	global_store_dwordx4 v[80:81], v[56:59], off offset:64
	s_waitcnt vmcnt(4)
	v_pk_fma_f32 v[52:53], v[52:53], v[140:141], v[136:137]
	s_waitcnt vmcnt(4)
	v_pk_fma_f32 v[54:55], v[54:55], v[142:143], v[138:139]
	global_store_dwordx4 v[80:81], v[52:55], off offset:128
	s_waitcnt vmcnt(3)
	v_pk_fma_f32 v[48:49], v[48:49], v[148:149], v[144:145]
	s_waitcnt vmcnt(3)
	v_pk_fma_f32 v[50:51], v[50:51], v[150:151], v[146:147]
	global_store_dwordx4 v[80:81], v[48:51], off offset:192
	s_nop 1
	v_or_b32_e32 v48, 16, v70
	v_mul_hi_i32 v49, v48, s11
	v_lshrrev_b32_e32 v50, 31, v49
	v_ashrrev_i32_e32 v49, 13, v49
	v_add_u32_e32 v54, v49, v50
	v_mad_i32_i24 v51, v54, s16, v48
	v_cmp_gt_i32_e32 vcc, s17, v51
	v_cmp_lt_i32_e64 s[0:1], s18, v51
	v_mov_b64_e32 v[48:49], s[40:41]
	s_and_saveexec_b64 s[8:9], s[0:1]
	s_xor_b64 s[0:1], exec, s[8:9]
	v_lshlrev_b32_e32 v48, 14, v54
	v_add3_u32 v50, v48, v51, s19
	v_mov_b64_e32 v[48:49], s[36:37]
	s_or_saveexec_b64 s[0:1], s[0:1]
	v_mov_b64_e32 v[52:53], s[92:93]
	s_xor_b64 exec, exec, s[0:1]
	v_lshl_add_u32 v50, v54, 8, v51
	v_mov_b64_e32 v[52:53], s[68:69]
	s_or_b64 exec, exec, s[0:1]
	v_ashrrev_i32_e32 v51, 31, v50
	v_mul_i32_i24_e32 v54, 0x1800, v54
	v_lshlrev_b64 v[50:51], 12, v[50:51]
	v_cndmask_b32_e32 v54, v54, v184, vcc
	v_lshl_add_u64 v[48:49], v[48:49], 0, v[50:51]
	v_ashrrev_i32_e32 v55, 31, v54
	v_lshl_add_u64 v[50:51], v[52:53], 0, v[50:51]
	v_lshl_add_u64 v[52:53], v[54:55], 2, s[6:7]
	v_lshl_add_u64 v[56:57], v[48:49], 0, v[64:65]
	v_lshl_add_u64 v[58:59], v[52:53], 0, v[64:65]
	v_lshl_add_u64 v[60:61], v[50:51], 0, v[64:65]
	global_load_dwordx4 v[156:159], v[56:57], off
	global_load_dwordx4 v[152:155], v[58:59], off
	global_load_dwordx4 v[132:135], v[56:57], off offset:64
	global_load_dwordx4 v[124:127], v[58:59], off offset:64
	global_load_dwordx4 v[136:139], v[56:57], off offset:128
	global_load_dwordx4 v[140:143], v[58:59], off offset:128
	global_load_dwordx4 v[144:147], v[56:57], off offset:192
	global_load_dwordx4 v[148:151], v[58:59], off offset:192
	s_waitcnt vmcnt(6)
;   __device__ __forceinline__ void operator()(const f32x4 (&acc)[4][4], int row0w, int col0w, int l15, int quad) const {
; #pragma unroll
;     for (int i = 0; i < 4; ++i) {
;       const int row = row0w + i * 16 + l15;
;       const int b = row / TPB, kidx = row - b * TPB;
;       const bool isc = kidx < 256;
;       const size_t off = isc ? (size_t)(b * 256 + kidx) * DM : (size_t)(b * 16384 + kidx - 256) * DM;
;       const float* src = (isc ? ctx_src : lat_src) + off;
;       float* dst = (isc ? ctx_dst : lat_dst) + off;
;       const float* g = gate + (isc ? 2 : b) * 6144;
; #pragma unroll
;       for (int j = 0; j < 4; ++j) {
;         const int n = col0w + j * 16 + quad * 4;
;         const float4 xo = *(const float4*)(src + n);
;         const float4 g4 = *(const float4*)(g + n);
;         float4 o;
;         o.x = xo.x + g4.x * acc[i][j][0];
;         o.y = xo.y + g4.y * acc[i][j][1];
;         o.z = xo.z + g4.z * acc[i][j][2];
;         o.w = xo.w + g4.w * acc[i][j][3];
;         *(float4*)(dst + n) = o;
;       }
;     }
;   }
	v_pk_fma_f32 v[44:45], v[44:45], v[152:153], v[156:157]
	s_waitcnt vmcnt(6)
	v_pk_fma_f32 v[46:47], v[46:47], v[154:155], v[158:159]
	global_store_dwordx4 v[60:61], v[44:47], off
	s_waitcnt vmcnt(5)
	v_pk_fma_f32 v[40:41], v[40:41], v[124:125], v[132:133]
	s_waitcnt vmcnt(5)
	v_pk_fma_f32 v[42:43], v[42:43], v[126:127], v[134:135]
	global_store_dwordx4 v[60:61], v[40:43], off offset:64
	s_waitcnt vmcnt(4)
	v_pk_fma_f32 v[36:37], v[36:37], v[140:141], v[136:137]
	s_waitcnt vmcnt(4)
	v_pk_fma_f32 v[38:39], v[38:39], v[142:143], v[138:139]
	global_store_dwordx4 v[60:61], v[36:39], off offset:128
	s_waitcnt vmcnt(3)
	v_pk_fma_f32 v[32:33], v[32:33], v[148:149], v[144:145]
	s_waitcnt vmcnt(3)
	v_pk_fma_f32 v[34:35], v[34:35], v[150:151], v[146:147]
	global_store_dwordx4 v[60:61], v[32:35], off offset:192
	s_nop 1
	v_or_b32_e32 v32, 32, v70
	v_mul_hi_i32 v33, v32, s11
	v_lshrrev_b32_e32 v34, 31, v33
	v_ashrrev_i32_e32 v33, 13, v33
	v_add_u32_e32 v38, v33, v34
	v_mad_i32_i24 v35, v38, s16, v32
	v_cmp_gt_i32_e32 vcc, s17, v35
	v_cmp_lt_i32_e64 s[0:1], s18, v35
	v_mov_b64_e32 v[32:33], s[40:41]
	s_and_saveexec_b64 s[8:9], s[0:1]
	s_xor_b64 s[0:1], exec, s[8:9]
	v_lshlrev_b32_e32 v32, 14, v38
	v_add3_u32 v34, v32, v35, s19
	v_mov_b64_e32 v[32:33], s[36:37]
	s_or_saveexec_b64 s[0:1], s[0:1]
	v_mov_b64_e32 v[36:37], s[92:93]
	s_xor_b64 exec, exec, s[0:1]
	v_lshl_add_u32 v34, v38, 8, v35
	v_mov_b64_e32 v[36:37], s[68:69]
	s_or_b64 exec, exec, s[0:1]
	v_ashrrev_i32_e32 v35, 31, v34
	v_mul_i32_i24_e32 v38, 0x1800, v38
	v_lshlrev_b64 v[34:35], 12, v[34:35]
	v_cndmask_b32_e32 v38, v38, v184, vcc
	v_lshl_add_u64 v[32:33], v[32:33], 0, v[34:35]
	v_ashrrev_i32_e32 v39, 31, v38
	v_lshl_add_u64 v[34:35], v[36:37], 0, v[34:35]
	v_lshl_add_u64 v[36:37], v[38:39], 2, s[6:7]
	v_lshl_add_u64 v[40:41], v[32:33], 0, v[64:65]
	v_lshl_add_u64 v[42:43], v[36:37], 0, v[64:65]
	v_lshl_add_u64 v[44:45], v[34:35], 0, v[64:65]
	global_load_dwordx4 v[156:159], v[40:41], off
	global_load_dwordx4 v[152:155], v[42:43], off
	global_load_dwordx4 v[132:135], v[40:41], off offset:64
	global_load_dwordx4 v[124:127], v[42:43], off offset:64
	global_load_dwordx4 v[136:139], v[40:41], off offset:128
	global_load_dwordx4 v[140:143], v[42:43], off offset:128
	global_load_dwordx4 v[144:147], v[40:41], off offset:192
	global_load_dwordx4 v[148:151], v[42:43], off offset:192
	s_waitcnt vmcnt(6)
	v_pk_fma_f32 v[28:29], v[28:29], v[152:153], v[156:157]
	s_waitcnt vmcnt(6)
	v_pk_fma_f32 v[30:31], v[30:31], v[154:155], v[158:159]
	global_store_dwordx4 v[44:45], v[28:31], off
	s_waitcnt vmcnt(5)
	v_pk_fma_f32 v[24:25], v[24:25], v[124:125], v[132:133]
	s_waitcnt vmcnt(5)
	v_pk_fma_f32 v[26:27], v[26:27], v[126:127], v[134:135]
	global_store_dwordx4 v[44:45], v[24:27], off offset:64
	s_waitcnt vmcnt(4)
	v_pk_fma_f32 v[20:21], v[20:21], v[140:141], v[136:137]
	s_waitcnt vmcnt(4)
	v_pk_fma_f32 v[22:23], v[22:23], v[142:143], v[138:139]
	global_store_dwordx4 v[44:45], v[20:23], off offset:128
	s_waitcnt vmcnt(3)
	v_pk_fma_f32 v[16:17], v[16:17], v[148:149], v[144:145]
	s_waitcnt vmcnt(3)
	v_pk_fma_f32 v[18:19], v[18:19], v[150:151], v[146:147]
	global_store_dwordx4 v[44:45], v[16:19], off offset:192
	s_nop 1
	v_or_b32_e32 v16, 48, v70
	v_mul_hi_i32 v17, v16, s11
	v_lshrrev_b32_e32 v18, 31, v17
	v_ashrrev_i32_e32 v17, 13, v17
	v_add_u32_e32 v19, v17, v18
	v_mad_i32_i24 v22, v19, s16, v16
	v_cmp_gt_i32_e32 vcc, s17, v22
	v_cmp_lt_i32_e64 s[0:1], s18, v22
	v_mov_b64_e32 v[16:17], s[40:41]
	s_and_saveexec_b64 s[8:9], s[0:1]
	s_xor_b64 s[0:1], exec, s[8:9]
	v_lshlrev_b32_e32 v16, 14, v19
	v_add3_u32 v18, v16, v22, s19
	v_mov_b64_e32 v[16:17], s[36:37]
	s_or_saveexec_b64 s[0:1], s[0:1]
	v_mov_b64_e32 v[20:21], s[92:93]
	s_xor_b64 exec, exec, s[0:1]
	s_cbranch_execz .LBB0_435
	v_lshl_add_u32 v18, v19, 8, v22
	v_mov_b64_e32 v[20:21], s[68:69]
	s_branch .LBB0_435

;   __device__ __forceinline__ void operator()(const f32x4 (&acc)[4][4], int row0w, int col0w, int l15, int quad) const {
; #pragma unroll
;     for (int i = 0; i < 4; ++i) {
;       const int row = row0w + i * 16 + l15;
;       const int b = row / TPB, kidx = row - b * TPB;
;       const bool isc = kidx < 256;
;       const size_t off = isc ? (size_t)(b * 256 + kidx) * DM : (size_t)(b * 16384 + kidx - 256) * DM;
;       const float* src = (isc ? ctx_src : lat_src) + off;
;       float* dst = (isc ? ctx_dst : lat_dst) + off;
;       const float* g = gate + (isc ? 2 : b) * 6144;
; #pragma unroll
;       for (int j = 0; j < 4; ++j) {
;         const int n = col0w + j * 16 + quad * 4;
;         const float4 xo = *(const float4*)(src + n);
;         const float4 g4 = *(const float4*)(g + n);
;         float4 o;
;         o.x = xo.x + g4.x * acc[i][j][0];
;         o.y = xo.y + g4.y * acc[i][j][1];
;         o.z = xo.z + g4.z * acc[i][j][2];
;         o.w = xo.w + g4.w * acc[i][j][3];
;         *(float4*)(dst + n) = o;
;       }
;     }
;   }
.LBB0_632:
	s_or_b64 exec, exec, s[0:1]
	v_mul_i32_i24_e32 v17, 0x1800, v20
	v_cndmask_b32_e32 v20, v17, v185, vcc
	v_ashrrev_i32_e32 v17, 31, v16
	v_ashrrev_i32_e32 v21, 31, v20
	v_lshlrev_b64 v[16:17], 12, v[16:17]
	v_lshl_add_u64 v[16:17], v[18:19], 0, v[16:17]
	v_lshl_add_u64 v[18:19], v[20:21], 2, s[4:5]
	v_lshl_add_u64 v[30:31], v[18:19], 0, v[64:65]
	v_lshl_add_u64 v[28:29], v[16:17], 0, v[64:65]
	global_load_dwordx4 v[156:159], v[30:31], off
	global_load_dwordx4 v[152:155], v[28:29], off
	global_load_dwordx4 v[132:135], v[28:29], off offset:64
	global_load_dwordx4 v[124:127], v[30:31], off offset:64
	global_load_dwordx4 v[136:139], v[30:31], off offset:128
	global_load_dwordx4 v[140:143], v[28:29], off offset:128
	global_load_dwordx4 v[144:147], v[28:29], off offset:192
	global_load_dwordx4 v[148:151], v[30:31], off offset:192
	s_add_i32 s12, s12, s90
	s_add_i32 s2, s2, s90
	s_cmp_ge_i32 s12, s84
	s_waitcnt vmcnt(6)
	v_pk_fma_f32 v[12:13], v[12:13], v[156:157], v[152:153]
	s_waitcnt vmcnt(6)
	v_pk_fma_f32 v[14:15], v[14:15], v[158:159], v[154:155]
	global_store_dwordx4 v[28:29], v[12:15], off
	s_waitcnt vmcnt(5)
	v_pk_fma_f32 v[8:9], v[8:9], v[124:125], v[132:133]
	s_waitcnt vmcnt(5)
	v_pk_fma_f32 v[10:11], v[10:11], v[126:127], v[134:135]
	global_store_dwordx4 v[28:29], v[8:11], off offset:64
	s_waitcnt vmcnt(4)
	v_pk_fma_f32 v[4:5], v[4:5], v[136:137], v[140:141]
	s_waitcnt vmcnt(4)
	v_pk_fma_f32 v[6:7], v[6:7], v[138:139], v[142:143]
	global_store_dwordx4 v[28:29], v[4:7], off offset:128
	s_waitcnt vmcnt(3)
	v_pk_fma_f32 v[0:1], v[0:1], v[148:149], v[144:145]
	s_waitcnt vmcnt(3)
	v_pk_fma_f32 v[2:3], v[2:3], v[150:151], v[146:147]
	global_store_dwordx4 v[28:29], v[0:3], off offset:192
	s_cbranch_scc1 .LBB0_653

;   __device__ __forceinline__ void operator()(const f32x4 (&acc)[4][4], int row0w, int col0w, int l15, int quad) const {
; #pragma unroll
;     for (int i = 0; i < 4; ++i) {
;       const int row = row0w + i * 16 + l15;
;       const int b = row / TPB, kidx = row - b * TPB;
;       const bool isc = kidx < 256;
;       const size_t off = isc ? (size_t)(b * 256 + kidx) * DM : (size_t)(b * 16384 + kidx - 256) * DM;
;       const float* src = (isc ? ctx_src : lat_src) + off;
;       float* dst = (isc ? ctx_dst : lat_dst) + off;
;       const float* g = gate + (isc ? 2 : b) * 6144;
; #pragma unroll
;       for (int j = 0; j < 4; ++j) {
;         const int n = col0w + j * 16 + quad * 4;
;         const float4 xo = *(const float4*)(src + n);
;         const float4 g4 = *(const float4*)(g + n);
;         float4 o;
;         o.x = xo.x + g4.x * acc[i][j][0];
;         o.y = xo.y + g4.y * acc[i][j][1];
;         o.z = xo.z + g4.z * acc[i][j][2];
;         o.w = xo.w + g4.w * acc[i][j][3];
;         *(float4*)(dst + n) = o;
;       }
;     }
;   }
.LBB0_637:
	s_waitcnt vmcnt(6)
	v_add_u32_e32 v68, s14, v174
	v_mul_hi_i32 v64, v68, s7
	v_lshrrev_b32_e32 v65, 31, v64
	v_ashrrev_i32_e32 v64, 13, v64
	v_add_u32_e32 v69, v64, v65
	v_mad_i32_i24 v65, v69, s8, v68
	v_cmp_gt_i32_e32 vcc, s9, v65
	v_cmp_lt_i32_e64 s[0:1], s10, v65
	s_and_saveexec_b64 s[14:15], s[0:1]
	s_xor_b64 s[0:1], exec, s[14:15]
	v_lshlrev_b32_e32 v64, 14, v69
	v_add3_u32 v64, v64, v65, s11
	s_or_saveexec_b64 s[0:1], s[0:1]
	v_mov_b64_e32 v[66:67], s[92:93]
	s_xor_b64 exec, exec, s[0:1]
	v_lshl_add_u32 v64, v69, 8, v65
	v_mov_b64_e32 v[66:67], s[68:69]
	s_or_b64 exec, exec, s[0:1]
	v_ashrrev_i32_e32 v65, 31, v64
	v_lshlrev_b64 v[64:65], 12, v[64:65]
	v_lshl_add_u64 v[66:67], v[66:67], 0, v[64:65]
	v_mul_i32_i24_e32 v64, 0x1800, v69
	v_or_b32_e32 v70, s13, v176
	v_cndmask_b32_e32 v64, v64, v185, vcc
	v_ashrrev_i32_e32 v71, 31, v70
	v_ashrrev_i32_e32 v65, 31, v64
	s_waitcnt vmcnt(3)
	v_lshl_add_u64 v[72:73], v[64:65], 2, s[4:5]
	v_lshlrev_b64 v[64:65], 2, v[70:71]
	v_lshl_add_u64 v[82:83], v[72:73], 0, v[64:65]
	v_lshl_add_u64 v[66:67], v[66:67], 0, v[64:65]
	global_load_dwordx4 v[156:159], v[82:83], off
	global_load_dwordx4 v[152:155], v[66:67], off
	global_load_dwordx4 v[132:135], v[66:67], off offset:64
	global_load_dwordx4 v[124:127], v[82:83], off offset:64
	global_load_dwordx4 v[136:139], v[82:83], off offset:128
	global_load_dwordx4 v[140:143], v[66:67], off offset:128
	global_load_dwordx4 v[144:147], v[66:67], off offset:192
	global_load_dwordx4 v[148:151], v[82:83], off offset:192
	s_waitcnt vmcnt(6)
	v_pk_fma_f32 v[60:61], v[60:61], v[156:157], v[152:153]
	s_waitcnt vmcnt(6)
	v_pk_fma_f32 v[62:63], v[62:63], v[158:159], v[154:155]
	global_store_dwordx4 v[66:67], v[60:63], off
	s_waitcnt vmcnt(5)
	v_pk_fma_f32 v[56:57], v[56:57], v[124:125], v[132:133]
	s_waitcnt vmcnt(5)
	v_pk_fma_f32 v[58:59], v[58:59], v[126:127], v[134:135]
	global_store_dwordx4 v[66:67], v[56:59], off offset:64
	s_waitcnt vmcnt(4)
	v_pk_fma_f32 v[52:53], v[52:53], v[136:137], v[140:141]
	s_waitcnt vmcnt(4)
	v_pk_fma_f32 v[54:55], v[54:55], v[138:139], v[142:143]
	global_store_dwordx4 v[66:67], v[52:55], off offset:128
	s_waitcnt vmcnt(3)
	v_pk_fma_f32 v[48:49], v[48:49], v[148:149], v[144:145]
	v_or_b32_e32 v53, 16, v68
	v_mul_hi_i32 v52, v53, s7
	v_lshrrev_b32_e32 v58, 31, v52
	v_ashrrev_i32_e32 v52, 13, v52
	v_add_u32_e32 v52, v52, v58
	v_mad_i32_i24 v53, v52, s8, v53
	v_cmp_gt_i32_e32 vcc, s9, v53
	s_waitcnt vmcnt(3)
	v_pk_fma_f32 v[50:51], v[50:51], v[150:151], v[146:147]
	v_cmp_lt_i32_e64 s[0:1], s10, v53
	global_store_dwordx4 v[66:67], v[48:51], off offset:192
	s_and_saveexec_b64 s[14:15], s[0:1]
	s_xor_b64 s[0:1], exec, s[14:15]
	v_lshlrev_b32_e32 v48, 14, v52
	v_add3_u32 v48, v48, v53, s11
	s_or_saveexec_b64 s[0:1], s[0:1]
	v_mov_b64_e32 v[50:51], s[92:93]
	s_xor_b64 exec, exec, s[0:1]
	v_lshl_add_u32 v48, v52, 8, v53
	v_mov_b64_e32 v[50:51], s[68:69]
	s_or_b64 exec, exec, s[0:1]
	v_ashrrev_i32_e32 v49, 31, v48
	v_lshlrev_b64 v[48:49], 12, v[48:49]
	v_lshl_add_u64 v[48:49], v[50:51], 0, v[48:49]
	v_mul_i32_i24_e32 v50, 0x1800, v52
	v_cndmask_b32_e32 v50, v50, v185, vcc
	v_ashrrev_i32_e32 v51, 31, v50
	v_lshl_add_u64 v[50:51], v[50:51], 2, s[4:5]
	v_lshl_add_u64 v[62:63], v[50:51], 0, v[64:65]
	v_lshl_add_u64 v[60:61], v[48:49], 0, v[64:65]
	global_load_dwordx4 v[156:159], v[62:63], off
	global_load_dwordx4 v[152:155], v[60:61], off
	global_load_dwordx4 v[132:135], v[60:61], off offset:64
	global_load_dwordx4 v[124:127], v[62:63], off offset:64
	global_load_dwordx4 v[136:139], v[62:63], off offset:128
	global_load_dwordx4 v[140:143], v[60:61], off offset:128
	global_load_dwordx4 v[144:147], v[60:61], off offset:192
	global_load_dwordx4 v[148:151], v[62:63], off offset:192
	s_waitcnt vmcnt(6)
;   __device__ __forceinline__ void operator()(const f32x4 (&acc)[4][4], int row0w, int col0w, int l15, int quad) const {
; #pragma unroll
;     for (int i = 0; i < 4; ++i) {
;       const int row = row0w + i * 16 + l15;
;       const int b = row / TPB, kidx = row - b * TPB;
;       const bool isc = kidx < 256;
;       const size_t off = isc ? (size_t)(b * 256 + kidx) * DM : (size_t)(b * 16384 + kidx - 256) * DM;
;       const float* src = (isc ? ctx_src : lat_src) + off;
;       float* dst = (isc ? ctx_dst : lat_dst) + off;
;       const float* g = gate + (isc ? 2 : b) * 6144;
; #pragma unroll
;       for (int j = 0; j < 4; ++j) {
;         const int n = col0w + j * 16 + quad * 4;
;         const float4 xo = *(const float4*)(src + n);
;         const float4 g4 = *(const float4*)(g + n);
;         float4 o;
;         o.x = xo.x + g4.x * acc[i][j][0];
;         o.y = xo.y + g4.y * acc[i][j][1];
;         o.z = xo.z + g4.z * acc[i][j][2];
;         o.w = xo.w + g4.w * acc[i][j][3];
;         *(float4*)(dst + n) = o;
;       }
;     }
;   }
	v_pk_fma_f32 v[44:45], v[44:45], v[156:157], v[152:153]
	s_waitcnt vmcnt(6)
	v_pk_fma_f32 v[46:47], v[46:47], v[158:159], v[154:155]
	global_store_dwordx4 v[60:61], v[44:47], off
	s_waitcnt vmcnt(5)
	v_pk_fma_f32 v[40:41], v[40:41], v[124:125], v[132:133]
	s_waitcnt vmcnt(5)
	v_pk_fma_f32 v[42:43], v[42:43], v[126:127], v[134:135]
	global_store_dwordx4 v[60:61], v[40:43], off offset:64
	s_waitcnt vmcnt(4)
	v_pk_fma_f32 v[36:37], v[36:37], v[136:137], v[140:141]
	s_waitcnt vmcnt(4)
	v_pk_fma_f32 v[38:39], v[38:39], v[138:139], v[142:143]
	global_store_dwordx4 v[60:61], v[36:39], off offset:128
	s_waitcnt vmcnt(3)
	v_pk_fma_f32 v[32:33], v[32:33], v[148:149], v[144:145]
	v_or_b32_e32 v37, 32, v68
	v_mul_hi_i32 v36, v37, s7
	v_lshrrev_b32_e32 v42, 31, v36
	v_ashrrev_i32_e32 v36, 13, v36
	v_add_u32_e32 v36, v36, v42
	v_mad_i32_i24 v37, v36, s8, v37
	v_cmp_gt_i32_e32 vcc, s9, v37
	s_waitcnt vmcnt(3)
	v_pk_fma_f32 v[34:35], v[34:35], v[150:151], v[146:147]
	v_cmp_lt_i32_e64 s[0:1], s10, v37
	global_store_dwordx4 v[60:61], v[32:35], off offset:192
	s_and_saveexec_b64 s[14:15], s[0:1]
	s_xor_b64 s[0:1], exec, s[14:15]
	v_lshlrev_b32_e32 v32, 14, v36
	v_add3_u32 v32, v32, v37, s11
	s_or_saveexec_b64 s[0:1], s[0:1]
	v_mov_b64_e32 v[34:35], s[92:93]
	s_xor_b64 exec, exec, s[0:1]
	v_lshl_add_u32 v32, v36, 8, v37
	v_mov_b64_e32 v[34:35], s[68:69]
	s_or_b64 exec, exec, s[0:1]
	v_ashrrev_i32_e32 v33, 31, v32
	v_lshlrev_b64 v[32:33], 12, v[32:33]
	v_lshl_add_u64 v[32:33], v[34:35], 0, v[32:33]
	v_mul_i32_i24_e32 v34, 0x1800, v36
	v_cndmask_b32_e32 v34, v34, v185, vcc
	v_ashrrev_i32_e32 v35, 31, v34
	v_lshl_add_u64 v[34:35], v[34:35], 2, s[4:5]
	v_lshl_add_u64 v[46:47], v[34:35], 0, v[64:65]
	v_lshl_add_u64 v[44:45], v[32:33], 0, v[64:65]
	global_load_dwordx4 v[156:159], v[46:47], off
	global_load_dwordx4 v[152:155], v[44:45], off
	global_load_dwordx4 v[132:135], v[44:45], off offset:64
	global_load_dwordx4 v[124:127], v[46:47], off offset:64
	global_load_dwordx4 v[136:139], v[46:47], off offset:128
	global_load_dwordx4 v[140:143], v[44:45], off offset:128
	global_load_dwordx4 v[144:147], v[44:45], off offset:192
	global_load_dwordx4 v[148:151], v[46:47], off offset:192
	s_waitcnt vmcnt(6)
	v_pk_fma_f32 v[28:29], v[28:29], v[156:157], v[152:153]
	s_waitcnt vmcnt(6)
	v_pk_fma_f32 v[30:31], v[30:31], v[158:159], v[154:155]
	global_store_dwordx4 v[44:45], v[28:31], off
	s_waitcnt vmcnt(5)
	v_pk_fma_f32 v[24:25], v[24:25], v[124:125], v[132:133]
	s_waitcnt vmcnt(5)
	v_pk_fma_f32 v[26:27], v[26:27], v[126:127], v[134:135]
	global_store_dwordx4 v[44:45], v[24:27], off offset:64
	s_waitcnt vmcnt(4)
	v_pk_fma_f32 v[20:21], v[20:21], v[136:137], v[140:141]
	s_waitcnt vmcnt(4)
	v_pk_fma_f32 v[22:23], v[22:23], v[138:139], v[142:143]
	global_store_dwordx4 v[44:45], v[20:23], off offset:128
	s_waitcnt vmcnt(3)
	v_pk_fma_f32 v[16:17], v[16:17], v[148:149], v[144:145]
	v_or_b32_e32 v21, 48, v68
	v_mul_hi_i32 v20, v21, s7
	v_lshrrev_b32_e32 v26, 31, v20
	v_ashrrev_i32_e32 v20, 13, v20
	v_add_u32_e32 v20, v20, v26
	v_mad_i32_i24 v21, v20, s8, v21
	v_cmp_gt_i32_e32 vcc, s9, v21
	s_waitcnt vmcnt(3)
	v_pk_fma_f32 v[18:19], v[18:19], v[150:151], v[146:147]
	v_cmp_lt_i32_e64 s[0:1], s10, v21
	global_store_dwordx4 v[44:45], v[16:19], off offset:192
	s_and_saveexec_b64 s[14:15], s[0:1]
	s_xor_b64 s[0:1], exec, s[14:15]
	v_lshlrev_b32_e32 v16, 14, v20
	v_add3_u32 v16, v16, v21, s11
	s_or_saveexec_b64 s[0:1], s[0:1]
	v_mov_b64_e32 v[18:19], s[92:93]
	s_xor_b64 exec, exec, s[0:1]
	s_cbranch_execz .LBB0_632
	v_lshl_add_u32 v16, v20, 8, v21
	v_mov_b64_e32 v[18:19], s[68:69]
	s_branch .LBB0_632

;   __device__ __forceinline__ void operator()(const f32x4 (&acc)[4][4], int row0w, int col0w, int l15, int quad) const {
; #pragma unroll
;     for (int i = 0; i < 4; ++i) {
;       const int row = row0w + i * 16 + l15;
;       const int b = row / TPB, kidx = row - b * TPB;
;       const bool isc = kidx < 256;
;       const size_t off = isc ? (size_t)(b * 256 + kidx) * DM : (size_t)(b * 16384 + kidx - 256) * DM;
;       const float* src = (isc ? ctx_src : lat_src) + off;
;       float* dst = (isc ? ctx_dst : lat_dst) + off;
;       const float* g = gate + (isc ? 2 : b) * 6144;
; #pragma unroll
;       for (int j = 0; j < 4; ++j) {
;         const int n = col0w + j * 16 + quad * 4;
;         const float4 xo = *(const float4*)(src + n);
;         const float4 g4 = *(const float4*)(g + n);
;         float4 o;
;         o.x = xo.x + g4.x * acc[i][j][0];
;         o.y = xo.y + g4.y * acc[i][j][1];
;         o.z = xo.z + g4.z * acc[i][j][2];
;         o.w = xo.w + g4.w * acc[i][j][3];
;         *(float4*)(dst + n) = o;
;       }
;     }
;   }
.LBB0_1418:
	s_or_b64 exec, exec, s[0:1]
	v_mul_i32_i24_e32 v17, 0x1800, v20
	v_cndmask_b32_e32 v20, v17, v180, vcc
	v_ashrrev_i32_e32 v17, 31, v16
	v_ashrrev_i32_e32 v21, 31, v20
	v_lshlrev_b64 v[16:17], 12, v[16:17]
	v_lshl_add_u64 v[16:17], v[18:19], 0, v[16:17]
	v_lshl_add_u64 v[18:19], v[20:21], 2, s[4:5]
	v_lshl_add_u64 v[30:31], v[18:19], 0, v[64:65]
	v_lshl_add_u64 v[28:29], v[16:17], 0, v[64:65]
	global_load_dwordx4 v[156:159], v[30:31], off
	global_load_dwordx4 v[152:155], v[28:29], off
	global_load_dwordx4 v[132:135], v[28:29], off offset:64
	global_load_dwordx4 v[124:127], v[30:31], off offset:64
	global_load_dwordx4 v[136:139], v[30:31], off offset:128
	global_load_dwordx4 v[140:143], v[28:29], off offset:128
	global_load_dwordx4 v[144:147], v[28:29], off offset:192
	global_load_dwordx4 v[148:151], v[30:31], off offset:192
	s_add_i32 s19, s19, s90
	s_add_i32 s11, s11, s90
	s_cmp_ge_i32 s19, s56
	s_waitcnt vmcnt(6)
	v_pk_fma_f32 v[12:13], v[12:13], v[156:157], v[152:153]
	s_waitcnt vmcnt(6)
	v_pk_fma_f32 v[14:15], v[14:15], v[158:159], v[154:155]
	global_store_dwordx4 v[28:29], v[12:15], off
	s_waitcnt vmcnt(5)
	v_pk_fma_f32 v[8:9], v[8:9], v[124:125], v[132:133]
	s_waitcnt vmcnt(5)
	v_pk_fma_f32 v[10:11], v[10:11], v[126:127], v[134:135]
	global_store_dwordx4 v[28:29], v[8:11], off offset:64
	s_waitcnt vmcnt(4)
	v_pk_fma_f32 v[4:5], v[4:5], v[136:137], v[140:141]
	s_waitcnt vmcnt(4)
	v_pk_fma_f32 v[6:7], v[6:7], v[138:139], v[142:143]
	global_store_dwordx4 v[28:29], v[4:7], off offset:128
	s_waitcnt vmcnt(3)
	v_pk_fma_f32 v[0:1], v[0:1], v[148:149], v[144:145]
	s_waitcnt vmcnt(3)
	v_pk_fma_f32 v[2:3], v[2:3], v[150:151], v[146:147]
	global_store_dwordx4 v[28:29], v[0:3], off offset:192
	s_cbranch_scc1 .LBB0_1439

;   __device__ __forceinline__ void operator()(const f32x4 (&acc)[4][4], int row0w, int col0w, int l15, int quad) const {
; #pragma unroll
;     for (int i = 0; i < 4; ++i) {
;       const int row = row0w + i * 16 + l15;
;       const int b = row / TPB, kidx = row - b * TPB;
;       const bool isc = kidx < 256;
;       const size_t off = isc ? (size_t)(b * 256 + kidx) * DM : (size_t)(b * 16384 + kidx - 256) * DM;
;       const float* src = (isc ? ctx_src : lat_src) + off;
;       float* dst = (isc ? ctx_dst : lat_dst) + off;
;       const float* g = gate + (isc ? 2 : b) * 6144;
; #pragma unroll
;       for (int j = 0; j < 4; ++j) {
;         const int n = col0w + j * 16 + quad * 4;
;         const float4 xo = *(const float4*)(src + n);
;         const float4 g4 = *(const float4*)(g + n);
;         float4 o;
;         o.x = xo.x + g4.x * acc[i][j][0];
;         o.y = xo.y + g4.y * acc[i][j][1];
;         o.z = xo.z + g4.z * acc[i][j][2];
;         o.w = xo.w + g4.w * acc[i][j][3];
;         *(float4*)(dst + n) = o;
;       }
;     }
;   }
.LBB0_1423:
	s_waitcnt vmcnt(6)
	v_add_u32_e32 v68, s0, v172
	v_mul_hi_i32 v64, v68, s15
	v_lshrrev_b32_e32 v65, 31, v64
	v_ashrrev_i32_e32 v64, 13, v64
	v_add_u32_e32 v69, v64, v65
	v_mad_i32_i24 v65, v69, s16, v68
	v_cmp_gt_i32_e32 vcc, s10, v65
	v_cmp_lt_i32_e64 s[0:1], s17, v65
	s_and_saveexec_b64 s[8:9], s[0:1]
	s_xor_b64 s[0:1], exec, s[8:9]
	v_lshlrev_b32_e32 v64, 14, v69
	v_add3_u32 v64, v64, v65, s18
	s_or_saveexec_b64 s[0:1], s[0:1]
	v_mov_b64_e32 v[66:67], s[92:93]
	s_xor_b64 exec, exec, s[0:1]
	v_lshl_add_u32 v64, v69, 8, v65
	v_mov_b64_e32 v[66:67], s[68:69]
	s_or_b64 exec, exec, s[0:1]
	v_ashrrev_i32_e32 v65, 31, v64
	v_lshlrev_b64 v[64:65], 12, v[64:65]
	v_lshl_add_u64 v[66:67], v[66:67], 0, v[64:65]
	v_mul_i32_i24_e32 v64, 0x1800, v69
	v_or_b32_e32 v70, s6, v174
	v_cndmask_b32_e32 v64, v64, v180, vcc
	v_ashrrev_i32_e32 v71, 31, v70
	v_ashrrev_i32_e32 v65, 31, v64
	s_waitcnt vmcnt(3)
	v_lshl_add_u64 v[72:73], v[64:65], 2, s[4:5]
	v_lshlrev_b64 v[64:65], 2, v[70:71]
	s_waitcnt vmcnt(2)
	v_lshl_add_u64 v[82:83], v[72:73], 0, v[64:65]
	v_lshl_add_u64 v[66:67], v[66:67], 0, v[64:65]
	global_load_dwordx4 v[156:159], v[82:83], off
	global_load_dwordx4 v[152:155], v[66:67], off
	global_load_dwordx4 v[132:135], v[66:67], off offset:64
	global_load_dwordx4 v[124:127], v[82:83], off offset:64
	global_load_dwordx4 v[136:139], v[82:83], off offset:128
	global_load_dwordx4 v[140:143], v[66:67], off offset:128
	global_load_dwordx4 v[144:147], v[66:67], off offset:192
	global_load_dwordx4 v[148:151], v[82:83], off offset:192
	s_waitcnt vmcnt(6)
	v_pk_fma_f32 v[60:61], v[60:61], v[156:157], v[152:153]
	s_waitcnt vmcnt(6)
	v_pk_fma_f32 v[62:63], v[62:63], v[158:159], v[154:155]
	global_store_dwordx4 v[66:67], v[60:63], off
	s_waitcnt vmcnt(5)
	v_pk_fma_f32 v[56:57], v[56:57], v[124:125], v[132:133]
	s_waitcnt vmcnt(5)
	v_pk_fma_f32 v[58:59], v[58:59], v[126:127], v[134:135]
	global_store_dwordx4 v[66:67], v[56:59], off offset:64
	s_waitcnt vmcnt(4)
	v_pk_fma_f32 v[52:53], v[52:53], v[136:137], v[140:141]
	s_waitcnt vmcnt(4)
	v_pk_fma_f32 v[54:55], v[54:55], v[138:139], v[142:143]
	global_store_dwordx4 v[66:67], v[52:55], off offset:128
	s_waitcnt vmcnt(3)
	v_pk_fma_f32 v[48:49], v[48:49], v[148:149], v[144:145]
	v_or_b32_e32 v53, 16, v68
	v_mul_hi_i32 v52, v53, s15
	v_lshrrev_b32_e32 v58, 31, v52
	v_ashrrev_i32_e32 v52, 13, v52
	v_add_u32_e32 v52, v52, v58
	v_mad_i32_i24 v53, v52, s16, v53
	v_cmp_gt_i32_e32 vcc, s10, v53
	s_waitcnt vmcnt(3)
	v_pk_fma_f32 v[50:51], v[50:51], v[150:151], v[146:147]
	v_cmp_lt_i32_e64 s[0:1], s17, v53
	global_store_dwordx4 v[66:67], v[48:51], off offset:192
	s_and_saveexec_b64 s[6:7], s[0:1]
	s_xor_b64 s[0:1], exec, s[6:7]
	v_lshlrev_b32_e32 v48, 14, v52
	v_add3_u32 v48, v48, v53, s18
	s_or_saveexec_b64 s[0:1], s[0:1]
	v_mov_b64_e32 v[50:51], s[92:93]
	s_xor_b64 exec, exec, s[0:1]
	v_lshl_add_u32 v48, v52, 8, v53
	v_mov_b64_e32 v[50:51], s[68:69]
	s_or_b64 exec, exec, s[0:1]
	v_ashrrev_i32_e32 v49, 31, v48
	v_lshlrev_b64 v[48:49], 12, v[48:49]
	v_lshl_add_u64 v[48:49], v[50:51], 0, v[48:49]
	v_mul_i32_i24_e32 v50, 0x1800, v52
	v_cndmask_b32_e32 v50, v50, v180, vcc
	v_ashrrev_i32_e32 v51, 31, v50
	v_lshl_add_u64 v[50:51], v[50:51], 2, s[4:5]
	v_lshl_add_u64 v[62:63], v[50:51], 0, v[64:65]
	v_lshl_add_u64 v[60:61], v[48:49], 0, v[64:65]
	global_load_dwordx4 v[156:159], v[62:63], off
	global_load_dwordx4 v[152:155], v[60:61], off
	global_load_dwordx4 v[132:135], v[60:61], off offset:64
	global_load_dwordx4 v[124:127], v[62:63], off offset:64
	global_load_dwordx4 v[136:139], v[62:63], off offset:128
	global_load_dwordx4 v[140:143], v[60:61], off offset:128
	global_load_dwordx4 v[144:147], v[60:61], off offset:192
	global_load_dwordx4 v[148:151], v[62:63], off offset:192
	s_waitcnt vmcnt(6)
;   __device__ __forceinline__ void operator()(const f32x4 (&acc)[4][4], int row0w, int col0w, int l15, int quad) const {
; #pragma unroll
;     for (int i = 0; i < 4; ++i) {
;       const int row = row0w + i * 16 + l15;
;       const int b = row / TPB, kidx = row - b * TPB;
;       const bool isc = kidx < 256;
;       const size_t off = isc ? (size_t)(b * 256 + kidx) * DM : (size_t)(b * 16384 + kidx - 256) * DM;
;       const float* src = (isc ? ctx_src : lat_src) + off;
;       float* dst = (isc ? ctx_dst : lat_dst) + off;
;       const float* g = gate + (isc ? 2 : b) * 6144;
; #pragma unroll
;       for (int j = 0; j < 4; ++j) {
;         const int n = col0w + j * 16 + quad * 4;
;         const float4 xo = *(const float4*)(src + n);
;         const float4 g4 = *(const float4*)(g + n);
;         float4 o;
;         o.x = xo.x + g4.x * acc[i][j][0];
;         o.y = xo.y + g4.y * acc[i][j][1];
;         o.z = xo.z + g4.z * acc[i][j][2];
;         o.w = xo.w + g4.w * acc[i][j][3];
;         *(float4*)(dst + n) = o;
;       }
;     }
;   }
	v_pk_fma_f32 v[44:45], v[44:45], v[156:157], v[152:153]
	s_waitcnt vmcnt(6)
	v_pk_fma_f32 v[46:47], v[46:47], v[158:159], v[154:155]
	global_store_dwordx4 v[60:61], v[44:47], off
	s_waitcnt vmcnt(5)
	v_pk_fma_f32 v[40:41], v[40:41], v[124:125], v[132:133]
	s_waitcnt vmcnt(5)
	v_pk_fma_f32 v[42:43], v[42:43], v[126:127], v[134:135]
	global_store_dwordx4 v[60:61], v[40:43], off offset:64
	s_waitcnt vmcnt(4)
	v_pk_fma_f32 v[36:37], v[36:37], v[136:137], v[140:141]
	s_waitcnt vmcnt(4)
	v_pk_fma_f32 v[38:39], v[38:39], v[138:139], v[142:143]
	global_store_dwordx4 v[60:61], v[36:39], off offset:128
	s_waitcnt vmcnt(3)
	v_pk_fma_f32 v[32:33], v[32:33], v[148:149], v[144:145]
	v_or_b32_e32 v37, 32, v68
	v_mul_hi_i32 v36, v37, s15
	v_lshrrev_b32_e32 v42, 31, v36
	v_ashrrev_i32_e32 v36, 13, v36
	v_add_u32_e32 v36, v36, v42
	v_mad_i32_i24 v37, v36, s16, v37
	v_cmp_gt_i32_e32 vcc, s10, v37
	s_waitcnt vmcnt(3)
	v_pk_fma_f32 v[34:35], v[34:35], v[150:151], v[146:147]
	v_cmp_lt_i32_e64 s[0:1], s17, v37
	global_store_dwordx4 v[60:61], v[32:35], off offset:192
	s_and_saveexec_b64 s[6:7], s[0:1]
	s_xor_b64 s[0:1], exec, s[6:7]
	v_lshlrev_b32_e32 v32, 14, v36
	v_add3_u32 v32, v32, v37, s18
	s_or_saveexec_b64 s[0:1], s[0:1]
	v_mov_b64_e32 v[34:35], s[92:93]
	s_xor_b64 exec, exec, s[0:1]
	v_lshl_add_u32 v32, v36, 8, v37
	v_mov_b64_e32 v[34:35], s[68:69]
	s_or_b64 exec, exec, s[0:1]
	v_ashrrev_i32_e32 v33, 31, v32
	v_lshlrev_b64 v[32:33], 12, v[32:33]
	v_lshl_add_u64 v[32:33], v[34:35], 0, v[32:33]
	v_mul_i32_i24_e32 v34, 0x1800, v36
	v_cndmask_b32_e32 v34, v34, v180, vcc
	v_ashrrev_i32_e32 v35, 31, v34
	v_lshl_add_u64 v[34:35], v[34:35], 2, s[4:5]
	v_lshl_add_u64 v[46:47], v[34:35], 0, v[64:65]
	v_lshl_add_u64 v[44:45], v[32:33], 0, v[64:65]
	global_load_dwordx4 v[156:159], v[46:47], off
	global_load_dwordx4 v[152:155], v[44:45], off
	global_load_dwordx4 v[132:135], v[44:45], off offset:64
	global_load_dwordx4 v[124:127], v[46:47], off offset:64
	global_load_dwordx4 v[136:139], v[46:47], off offset:128
	global_load_dwordx4 v[140:143], v[44:45], off offset:128
	global_load_dwordx4 v[144:147], v[44:45], off offset:192
	global_load_dwordx4 v[148:151], v[46:47], off offset:192
	s_waitcnt vmcnt(6)
	v_pk_fma_f32 v[28:29], v[28:29], v[156:157], v[152:153]
	s_waitcnt vmcnt(6)
	v_pk_fma_f32 v[30:31], v[30:31], v[158:159], v[154:155]
	global_store_dwordx4 v[44:45], v[28:31], off
	s_waitcnt vmcnt(5)
	v_pk_fma_f32 v[24:25], v[24:25], v[124:125], v[132:133]
	s_waitcnt vmcnt(5)
	v_pk_fma_f32 v[26:27], v[26:27], v[126:127], v[134:135]
	global_store_dwordx4 v[44:45], v[24:27], off offset:64
	s_waitcnt vmcnt(4)
	v_pk_fma_f32 v[20:21], v[20:21], v[136:137], v[140:141]
	s_waitcnt vmcnt(4)
	v_pk_fma_f32 v[22:23], v[22:23], v[138:139], v[142:143]
	global_store_dwordx4 v[44:45], v[20:23], off offset:128
	s_waitcnt vmcnt(3)
	v_pk_fma_f32 v[16:17], v[16:17], v[148:149], v[144:145]
	v_or_b32_e32 v21, 48, v68
	v_mul_hi_i32 v20, v21, s15
	v_lshrrev_b32_e32 v26, 31, v20
	v_ashrrev_i32_e32 v20, 13, v20
	v_add_u32_e32 v20, v20, v26
	v_mad_i32_i24 v21, v20, s16, v21
	v_cmp_gt_i32_e32 vcc, s10, v21
	s_waitcnt vmcnt(3)
	v_pk_fma_f32 v[18:19], v[18:19], v[150:151], v[146:147]
	v_cmp_lt_i32_e64 s[0:1], s17, v21
	global_store_dwordx4 v[44:45], v[16:19], off offset:192
	s_and_saveexec_b64 s[6:7], s[0:1]
	s_xor_b64 s[0:1], exec, s[6:7]
	v_lshlrev_b32_e32 v16, 14, v20
	v_add3_u32 v16, v16, v21, s18
	s_or_saveexec_b64 s[0:1], s[0:1]
	v_mov_b64_e32 v[18:19], s[92:93]
	s_xor_b64 exec, exec, s[0:1]
	s_cbranch_execz .LBB0_1418
	v_lshl_add_u32 v16, v20, 8, v21
	v_mov_b64_e32 v[18:19], s[68:69]
	s_branch .LBB0_1418

;   __device__ __forceinline__ void operator()(const f32x4 (&acc)[4][4], int row0w, int col0w, int l15, int quad) const {
; #pragma unroll
;     for (int i = 0; i < 4; ++i) {
;       const int row = row0w + i * 16 + l15;
;       const int b = row / TPB, kidx = row - b * TPB;
;       const bool isc = kidx < 256;
;       const size_t off = isc ? (size_t)(b * 256 + kidx) * DM : (size_t)(b * 16384 + kidx - 256) * DM;
;       const float* src = (isc ? ctx_src : lat_src) + off;
;       float* dst = (isc ? ctx_dst : lat_dst) + off;
;       const float* g = gate + (isc ? 2 : b) * 6144;
; #pragma unroll
;       for (int j = 0; j < 4; ++j) {
;         const int n = col0w + j * 16 + quad * 4;
;         const float4 xo = *(const float4*)(src + n);
;         const float4 g4 = *(const float4*)(g + n);
;         float4 o;
;         o.x = xo.x + g4.x * acc[i][j][0];
;         o.y = xo.y + g4.y * acc[i][j][1];
;         o.z = xo.z + g4.z * acc[i][j][2];
;         o.w = xo.w + g4.w * acc[i][j][3];
;         *(float4*)(dst + n) = o;
;       }
;     }
;   }
.LBB0_1615:
	s_or_b64 exec, exec, s[0:1]
	v_mul_i32_i24_e32 v17, 0x1800, v20
	v_cndmask_b32_e32 v20, v17, v177, vcc
	v_ashrrev_i32_e32 v17, 31, v16
	v_ashrrev_i32_e32 v21, 31, v20
	v_lshlrev_b64 v[16:17], 12, v[16:17]
	v_lshl_add_u64 v[16:17], v[18:19], 0, v[16:17]
	v_lshl_add_u64 v[18:19], v[20:21], 2, s[2:3]
	v_lshl_add_u64 v[30:31], v[18:19], 0, v[64:65]
	v_lshl_add_u64 v[28:29], v[16:17], 0, v[64:65]
	global_load_dwordx4 v[156:159], v[30:31], off
	global_load_dwordx4 v[152:155], v[28:29], off
	global_load_dwordx4 v[132:135], v[28:29], off offset:64
	global_load_dwordx4 v[124:127], v[30:31], off offset:64
	global_load_dwordx4 v[136:139], v[30:31], off offset:128
	global_load_dwordx4 v[140:143], v[28:29], off offset:128
	global_load_dwordx4 v[144:147], v[28:29], off offset:192
	global_load_dwordx4 v[148:151], v[30:31], off offset:192
	s_add_i32 s91, s91, s90
	s_add_i32 s4, s4, s90
	s_cmp_ge_i32 s91, s56
	s_waitcnt vmcnt(6)
	v_pk_fma_f32 v[12:13], v[12:13], v[156:157], v[152:153]
	s_waitcnt vmcnt(6)
	v_pk_fma_f32 v[14:15], v[14:15], v[158:159], v[154:155]
	global_store_dwordx4 v[28:29], v[12:15], off
	s_waitcnt vmcnt(5)
	v_pk_fma_f32 v[8:9], v[8:9], v[124:125], v[132:133]
	s_waitcnt vmcnt(5)
	v_pk_fma_f32 v[10:11], v[10:11], v[126:127], v[134:135]
	global_store_dwordx4 v[28:29], v[8:11], off offset:64
	s_waitcnt vmcnt(4)
	v_pk_fma_f32 v[4:5], v[4:5], v[136:137], v[140:141]
	s_waitcnt vmcnt(4)
	v_pk_fma_f32 v[6:7], v[6:7], v[138:139], v[142:143]
	global_store_dwordx4 v[28:29], v[4:7], off offset:128
	s_waitcnt vmcnt(3)
	v_pk_fma_f32 v[0:1], v[0:1], v[148:149], v[144:145]
	s_waitcnt vmcnt(3)
	v_pk_fma_f32 v[2:3], v[2:3], v[150:151], v[146:147]
	global_store_dwordx4 v[28:29], v[0:3], off offset:192
	s_cbranch_scc1 .LBB0_1636

;   __device__ __forceinline__ void operator()(const f32x4 (&acc)[4][4], int row0w, int col0w, int l15, int quad) const {
; #pragma unroll
;     for (int i = 0; i < 4; ++i) {
;       const int row = row0w + i * 16 + l15;
;       const int b = row / TPB, kidx = row - b * TPB;
;       const bool isc = kidx < 256;
;       const size_t off = isc ? (size_t)(b * 256 + kidx) * DM : (size_t)(b * 16384 + kidx - 256) * DM;
;       const float* src = (isc ? ctx_src : lat_src) + off;
;       float* dst = (isc ? ctx_dst : lat_dst) + off;
;       const float* g = gate + (isc ? 2 : b) * 6144;
; #pragma unroll
;       for (int j = 0; j < 4; ++j) {
;         const int n = col0w + j * 16 + quad * 4;
;         const float4 xo = *(const float4*)(src + n);
;         const float4 g4 = *(const float4*)(g + n);
;         float4 o;
;         o.x = xo.x + g4.x * acc[i][j][0];
;         o.y = xo.y + g4.y * acc[i][j][1];
;         o.z = xo.z + g4.z * acc[i][j][2];
;         o.w = xo.w + g4.w * acc[i][j][3];
;         *(float4*)(dst + n) = o;
;       }
;     }
;   }
.LBB0_1620:
	s_waitcnt vmcnt(3)
	v_add_u32_e32 v68, s14, v169
	v_mul_hi_i32 v64, v68, s9
	v_lshrrev_b32_e32 v65, 31, v64
	v_ashrrev_i32_e32 v64, 13, v64
	v_add_u32_e32 v69, v64, v65
	v_mad_i32_i24 v65, v69, s10, v68
	v_cmp_gt_i32_e32 vcc, s5, v65
	v_cmp_lt_i32_e64 s[0:1], s11, v65
	s_and_saveexec_b64 s[14:15], s[0:1]
	s_xor_b64 s[0:1], exec, s[14:15]
	v_lshlrev_b32_e32 v64, 14, v69
	v_add3_u32 v64, v64, v65, s12
	s_or_saveexec_b64 s[0:1], s[0:1]
	v_mov_b64_e32 v[66:67], s[92:93]
	s_xor_b64 exec, exec, s[0:1]
	v_lshl_add_u32 v64, v69, 8, v65
	v_mov_b64_e32 v[66:67], s[68:69]
	s_or_b64 exec, exec, s[0:1]
	v_ashrrev_i32_e32 v65, 31, v64
	v_lshlrev_b64 v[64:65], 12, v[64:65]
	v_lshl_add_u64 v[66:67], v[66:67], 0, v[64:65]
	v_mul_i32_i24_e32 v64, 0x1800, v69
	v_or_b32_e32 v70, s13, v171
	v_cndmask_b32_e32 v64, v64, v177, vcc
	v_ashrrev_i32_e32 v71, 31, v70
	v_ashrrev_i32_e32 v65, 31, v64
	v_lshl_add_u64 v[72:73], v[64:65], 2, s[2:3]
	v_lshlrev_b64 v[64:65], 2, v[70:71]
	v_lshl_add_u64 v[82:83], v[72:73], 0, v[64:65]
	v_lshl_add_u64 v[66:67], v[66:67], 0, v[64:65]
	global_load_dwordx4 v[156:159], v[82:83], off
	global_load_dwordx4 v[152:155], v[66:67], off
	global_load_dwordx4 v[132:135], v[66:67], off offset:64
	global_load_dwordx4 v[124:127], v[82:83], off offset:64
	global_load_dwordx4 v[136:139], v[82:83], off offset:128
	global_load_dwordx4 v[140:143], v[66:67], off offset:128
	global_load_dwordx4 v[144:147], v[66:67], off offset:192
	global_load_dwordx4 v[148:151], v[82:83], off offset:192
	s_waitcnt vmcnt(6)
	v_pk_fma_f32 v[60:61], v[60:61], v[156:157], v[152:153]
	s_waitcnt vmcnt(6)
	v_pk_fma_f32 v[62:63], v[62:63], v[158:159], v[154:155]
	global_store_dwordx4 v[66:67], v[60:63], off
	s_waitcnt vmcnt(5)
	v_pk_fma_f32 v[56:57], v[56:57], v[124:125], v[132:133]
	s_waitcnt vmcnt(5)
	v_pk_fma_f32 v[58:59], v[58:59], v[126:127], v[134:135]
	global_store_dwordx4 v[66:67], v[56:59], off offset:64
	s_waitcnt vmcnt(4)
	v_pk_fma_f32 v[52:53], v[52:53], v[136:137], v[140:141]
	s_waitcnt vmcnt(4)
	v_pk_fma_f32 v[54:55], v[54:55], v[138:139], v[142:143]
	global_store_dwordx4 v[66:67], v[52:55], off offset:128
	s_waitcnt vmcnt(3)
	v_pk_fma_f32 v[48:49], v[48:49], v[148:149], v[144:145]
	v_or_b32_e32 v53, 16, v68
	v_mul_hi_i32 v52, v53, s9
	v_lshrrev_b32_e32 v58, 31, v52
	v_ashrrev_i32_e32 v52, 13, v52
	v_add_u32_e32 v52, v52, v58
	v_mad_i32_i24 v53, v52, s10, v53
	v_cmp_gt_i32_e32 vcc, s5, v53
	s_waitcnt vmcnt(3)
	v_pk_fma_f32 v[50:51], v[50:51], v[150:151], v[146:147]
	v_cmp_lt_i32_e64 s[0:1], s11, v53
	global_store_dwordx4 v[66:67], v[48:51], off offset:192
	s_and_saveexec_b64 s[14:15], s[0:1]
	s_xor_b64 s[0:1], exec, s[14:15]
	v_lshlrev_b32_e32 v48, 14, v52
	v_add3_u32 v48, v48, v53, s12
	s_or_saveexec_b64 s[0:1], s[0:1]
	v_mov_b64_e32 v[50:51], s[92:93]
	s_xor_b64 exec, exec, s[0:1]
	v_lshl_add_u32 v48, v52, 8, v53
	v_mov_b64_e32 v[50:51], s[68:69]
	s_or_b64 exec, exec, s[0:1]
	v_ashrrev_i32_e32 v49, 31, v48
	v_lshlrev_b64 v[48:49], 12, v[48:49]
	v_lshl_add_u64 v[48:49], v[50:51], 0, v[48:49]
	v_mul_i32_i24_e32 v50, 0x1800, v52
	v_cndmask_b32_e32 v50, v50, v177, vcc
	v_ashrrev_i32_e32 v51, 31, v50
	v_lshl_add_u64 v[50:51], v[50:51], 2, s[2:3]
	v_lshl_add_u64 v[62:63], v[50:51], 0, v[64:65]
	v_lshl_add_u64 v[60:61], v[48:49], 0, v[64:65]
	global_load_dwordx4 v[156:159], v[62:63], off
	global_load_dwordx4 v[152:155], v[60:61], off
	global_load_dwordx4 v[132:135], v[60:61], off offset:64
	global_load_dwordx4 v[124:127], v[62:63], off offset:64
	global_load_dwordx4 v[136:139], v[62:63], off offset:128
	global_load_dwordx4 v[140:143], v[60:61], off offset:128
	global_load_dwordx4 v[144:147], v[60:61], off offset:192
	global_load_dwordx4 v[148:151], v[62:63], off offset:192
	s_waitcnt vmcnt(6)
;   __device__ __forceinline__ void operator()(const f32x4 (&acc)[4][4], int row0w, int col0w, int l15, int quad) const {
; #pragma unroll
;     for (int i = 0; i < 4; ++i) {
;       const int row = row0w + i * 16 + l15;
;       const int b = row / TPB, kidx = row - b * TPB;
;       const bool isc = kidx < 256;
;       const size_t off = isc ? (size_t)(b * 256 + kidx) * DM : (size_t)(b * 16384 + kidx - 256) * DM;
;       const float* src = (isc ? ctx_src : lat_src) + off;
;       float* dst = (isc ? ctx_dst : lat_dst) + off;
;       const float* g = gate + (isc ? 2 : b) * 6144;
; #pragma unroll
;       for (int j = 0; j < 4; ++j) {
;         const int n = col0w + j * 16 + quad * 4;
;         const float4 xo = *(const float4*)(src + n);
;         const float4 g4 = *(const float4*)(g + n);
;         float4 o;
;         o.x = xo.x + g4.x * acc[i][j][0];
;         o.y = xo.y + g4.y * acc[i][j][1];
;         o.z = xo.z + g4.z * acc[i][j][2];
;         o.w = xo.w + g4.w * acc[i][j][3];
;         *(float4*)(dst + n) = o;
;       }
;     }
;   }
	v_pk_fma_f32 v[44:45], v[44:45], v[156:157], v[152:153]
	s_waitcnt vmcnt(6)
	v_pk_fma_f32 v[46:47], v[46:47], v[158:159], v[154:155]
	global_store_dwordx4 v[60:61], v[44:47], off
	s_waitcnt vmcnt(5)
	v_pk_fma_f32 v[40:41], v[40:41], v[124:125], v[132:133]
	s_waitcnt vmcnt(5)
	v_pk_fma_f32 v[42:43], v[42:43], v[126:127], v[134:135]
	global_store_dwordx4 v[60:61], v[40:43], off offset:64
	s_waitcnt vmcnt(4)
	v_pk_fma_f32 v[36:37], v[36:37], v[136:137], v[140:141]
	s_waitcnt vmcnt(4)
	v_pk_fma_f32 v[38:39], v[38:39], v[138:139], v[142:143]
	global_store_dwordx4 v[60:61], v[36:39], off offset:128
	s_waitcnt vmcnt(3)
	v_pk_fma_f32 v[32:33], v[32:33], v[148:149], v[144:145]
	v_or_b32_e32 v37, 32, v68
	v_mul_hi_i32 v36, v37, s9
	v_lshrrev_b32_e32 v42, 31, v36
	v_ashrrev_i32_e32 v36, 13, v36
	v_add_u32_e32 v36, v36, v42
	v_mad_i32_i24 v37, v36, s10, v37
	v_cmp_gt_i32_e32 vcc, s5, v37
	s_waitcnt vmcnt(3)
	v_pk_fma_f32 v[34:35], v[34:35], v[150:151], v[146:147]
	v_cmp_lt_i32_e64 s[0:1], s11, v37
	global_store_dwordx4 v[60:61], v[32:35], off offset:192
	s_and_saveexec_b64 s[14:15], s[0:1]
	s_xor_b64 s[0:1], exec, s[14:15]
	v_lshlrev_b32_e32 v32, 14, v36
	v_add3_u32 v32, v32, v37, s12
	s_or_saveexec_b64 s[0:1], s[0:1]
	v_mov_b64_e32 v[34:35], s[92:93]
	s_xor_b64 exec, exec, s[0:1]
	v_lshl_add_u32 v32, v36, 8, v37
	v_mov_b64_e32 v[34:35], s[68:69]
	s_or_b64 exec, exec, s[0:1]
	v_ashrrev_i32_e32 v33, 31, v32
	v_lshlrev_b64 v[32:33], 12, v[32:33]
	v_lshl_add_u64 v[32:33], v[34:35], 0, v[32:33]
	v_mul_i32_i24_e32 v34, 0x1800, v36
	v_cndmask_b32_e32 v34, v34, v177, vcc
	v_ashrrev_i32_e32 v35, 31, v34
	v_lshl_add_u64 v[34:35], v[34:35], 2, s[2:3]
	v_lshl_add_u64 v[46:47], v[34:35], 0, v[64:65]
	v_lshl_add_u64 v[44:45], v[32:33], 0, v[64:65]
	global_load_dwordx4 v[156:159], v[46:47], off
	global_load_dwordx4 v[152:155], v[44:45], off
	global_load_dwordx4 v[132:135], v[44:45], off offset:64
	global_load_dwordx4 v[124:127], v[46:47], off offset:64
	global_load_dwordx4 v[136:139], v[46:47], off offset:128
	global_load_dwordx4 v[140:143], v[44:45], off offset:128
	global_load_dwordx4 v[144:147], v[44:45], off offset:192
	global_load_dwordx4 v[148:151], v[46:47], off offset:192
	s_waitcnt vmcnt(6)
	v_pk_fma_f32 v[28:29], v[28:29], v[156:157], v[152:153]
	s_waitcnt vmcnt(6)
	v_pk_fma_f32 v[30:31], v[30:31], v[158:159], v[154:155]
	global_store_dwordx4 v[44:45], v[28:31], off
	s_waitcnt vmcnt(5)
	v_pk_fma_f32 v[24:25], v[24:25], v[124:125], v[132:133]
	s_waitcnt vmcnt(5)
	v_pk_fma_f32 v[26:27], v[26:27], v[126:127], v[134:135]
	global_store_dwordx4 v[44:45], v[24:27], off offset:64
	s_waitcnt vmcnt(4)
	v_pk_fma_f32 v[20:21], v[20:21], v[136:137], v[140:141]
	s_waitcnt vmcnt(4)
	v_pk_fma_f32 v[22:23], v[22:23], v[138:139], v[142:143]
	global_store_dwordx4 v[44:45], v[20:23], off offset:128
	s_waitcnt vmcnt(3)
	v_pk_fma_f32 v[16:17], v[16:17], v[148:149], v[144:145]
	v_or_b32_e32 v21, 48, v68
	v_mul_hi_i32 v20, v21, s9
	v_lshrrev_b32_e32 v26, 31, v20
	v_ashrrev_i32_e32 v20, 13, v20
	v_add_u32_e32 v20, v20, v26
	v_mad_i32_i24 v21, v20, s10, v21
	v_cmp_gt_i32_e32 vcc, s5, v21
	s_waitcnt vmcnt(3)
	v_pk_fma_f32 v[18:19], v[18:19], v[150:151], v[146:147]
	v_cmp_lt_i32_e64 s[0:1], s11, v21
	global_store_dwordx4 v[44:45], v[16:19], off offset:192
	s_and_saveexec_b64 s[14:15], s[0:1]
	s_xor_b64 s[0:1], exec, s[14:15]
	v_lshlrev_b32_e32 v16, 14, v20
	v_add3_u32 v16, v16, v21, s12
	s_or_saveexec_b64 s[0:1], s[0:1]
	v_mov_b64_e32 v[18:19], s[92:93]
	s_xor_b64 exec, exec, s[0:1]
	s_cbranch_execz .LBB0_1615
	v_lshl_add_u32 v16, v20, 8, v21
	v_mov_b64_e32 v[18:19], s[68:69]
	s_branch .LBB0_1615
